# NSA unit: branch-gate values fetched early in the unit (gate prefetch) on top of the phase-9/phase-6 row-loop changes
# speedup vs baseline: 1.0002x; 1.0002x over previous
;     ...
;         const float g0 = gp[0] * invl;
; #pragma unroll
;         for (int dt = 0; dt < 2; ++dt)
; #pragma unroll
;             for (int i = 0; i < 16; ++i) oacc[dt][i] = g0 * oc[dt][i];
;         __syncthreads();
;     }
;     {
;         unsigned uk8[8]; bool val8[8];
;         const int j = lane;
; #pragma unroll
;         for (int qq = 0; qq < 8; ++qq) {
;             const int rr = 8 * w + qq, qp = q0 + rr, cur = qp >> 6;
;             const bool valid = j <= cur;
;             float v = 0.f;
;             if (valid) {
;                 const float* ip = IMPW + ((rr >> 5) * 4 * 32 + (rr & 31)) * 64 + j;
;                 const float* fp = FT + ((rr >> 5) * 4 * 32 + (rr & 31)) * 4 + (j >> 4);
;                 v = ((ip[0] * fp[0] + ip[2048] * fp[128]) + ip[4096] * fp[256]) + ip[6144] * fp[384];
;             }
.LBB0_506:
	s_or_b64 exec, exec, s[4:5]
	v_lshlrev_b32_e32 v34, 12, v85
	v_mov_b32_e32 v35, v173
	v_lshl_add_u64 v[182:183], v[178:179], 0, v[34:35]
	v_mov_b64_e32 v[34:35], s[76:77]
	s_movk_i32 s4, 0x60
	v_mad_u64_u32 v[34:35], s[2:3], v182, s4, v[34:35]
	v_mad_i32_i24 v35, v183, s4, v35
	v_lshlrev_b32_e32 v36, 2, v86
	v_mov_b32_e32 v37, v173
	v_lshl_add_u64 v[184:185], v[34:35], 0, v[36:37]
	global_load_dword v179, v[184:185], off
	global_load_dword v239, v[184:185], off offset:8
	v_lshlrev_b32_e32 v34, 5, v82
	v_and_b32_e32 v47, 0xffffff80, v34
	v_lshrrev_b32_e32 v34, 2, v84
	v_and_b32_e32 v34, 12, v34
	v_add_u32_e32 v52, s74, v34
	v_add_u32_e32 v34, v83, v123
	v_ashrrev_i32_e32 v50, 6, v34
	v_lshl_add_u32 v51, v84, 2, 0
	v_cmp_le_i32_e32 vcc, v84, v50
	v_mov_b32_e32 v36, 0xff800000
	v_mov_b32_e32 v34, 0xff800000
	s_waitcnt lgkmcnt(0)
	s_barrier
	s_and_saveexec_b64 s[4:5], vcc
	s_cbranch_execz .LBB0_508
	v_and_or_b32 v34, v83, 24, v47
	v_lshl_add_u32 v37, v34, 8, v51
	v_lshl_add_u32 v42, v34, 4, v52
	ds_read2st64_b32 v[34:35], v37 offset0:144 offset1:176
	ds_read2st64_b32 v[38:39], v42 offset1:2
	ds_read2st64_b32 v[40:41], v37 offset0:208 offset1:240
	ds_read2st64_b32 v[42:43], v42 offset0:4 offset1:6
	s_waitcnt lgkmcnt(2)
	v_mul_f32_e32 v44, v35, v39
	v_pk_fma_f32 v[34:35], v[34:35], v[38:39], v[44:45] op_sel_hi:[1,1,0]
	s_waitcnt lgkmcnt(0)
	v_mul_f32_e32 v38, v41, v43
	v_pk_fma_f32 v[34:35], v[40:41], v[42:43], v[34:35]
	s_nop 0
	v_pk_add_f32 v[34:35], v[34:35], v[38:39] op_sel_hi:[1,0]

; DI float xhalf_sum(float x) { auto rr = __builtin_amdgcn_permlane32_swap(__float_as_uint(x), __float_as_uint(x), false, false); return __uint_as_float(rr[0]) + __uint_as_float(rr[1]); }
; DI float hsum16(const f32x16& v) {
;     const f32x8 a = __builtin_shufflevector(v, v, 0, 1, 2, 3, 4, 5, 6, 7) + __builtin_shufflevector(v, v, 8, 9, 10, 11, 12, 13, 14, 15);
;     const f32x4 b = __builtin_shufflevector(a, a, 0, 1, 2, 3) + __builtin_shufflevector(a, a, 4, 5, 6, 7);
;     return (b[0] + b[1]) + (b[2] + b[3]);
; }
;     ...
;         const float l = xhalf_sum(hsum16(lv));
;         const float sc = l > 0.f ? gp[1] / l : 0.f;
.LBB0_557:
	v_pk_add_f32 v[70:71], v[70:71], v[78:79]
	v_pk_add_f32 v[72:73], v[72:73], v[80:81]
	v_pk_add_f32 v[68:69], v[68:69], v[76:77]
	v_pk_add_f32 v[66:67], v[66:67], v[74:75]
	v_pk_add_f32 v[68:69], v[68:69], v[72:73]
	v_pk_add_f32 v[66:67], v[66:67], v[70:71]
	v_lshlrev_b32_e32 v82, 18, v122
	v_pk_mov_b32 v[70:71], v[66:67], v[68:69] op_sel:[1,0]
	v_mov_b32_e32 v67, v69
	v_pk_add_f32 v[66:67], v[70:71], v[66:67]
	v_mov_b32_e32 v186, 0
	v_pk_add_f32 v[66:67], v[66:67], v[66:67] op_sel:[0,1] op_sel_hi:[1,0]
	s_nop 0
	v_mov_b32_e32 v67, v66
	s_nop 1
	v_permlane32_swap_b32_e32 v66, v67
	v_add_f32_e32 v66, v66, v67
	v_cmp_lt_f32_e32 vcc, 0, v66
	s_and_saveexec_b64 s[4:5], vcc
	s_cbranch_execz .LBB0_559
	s_waitcnt vmcnt(0)
	v_mov_b32_e32 v67, v192

;     ...
;         const float sc = l > 0.f ? gp[1] / l : 0.f;
	v_div_scale_f32 v68, s[2:3], v66, v66, v67
	v_rcp_f32_e32 v69, v68
	v_div_scale_f32 v70, vcc, v67, v66, v67
	v_fma_f32 v71, -v68, v69, 1.0
	v_fmac_f32_e32 v69, v71, v69
	v_mul_f32_e32 v71, v70, v69
	v_fma_f32 v72, -v68, v71, v70
	v_fmac_f32_e32 v71, v72, v69
	v_fma_f32 v68, -v68, v71, v70
	v_div_fmas_f32 v68, v68, v69, v71
	v_div_fixup_f32 v186, v68, v66, v67

; DI float xhalf_sum(float x) { auto rr = __builtin_amdgcn_permlane32_swap(__float_as_uint(x), __float_as_uint(x), false, false); return __uint_as_float(rr[0]) + __uint_as_float(rr[1]); }
;     ...
;         const float l = xhalf_sum(hsum16(lv));
;         const float sc = l > 0.f ? gp[2] / l : 0.f;
.LBB0_575:
	s_or_b64 exec, exec, s[8:9]
	v_pk_add_f32 v[102:103], v[102:103], v[110:111]
	v_pk_add_f32 v[104:105], v[104:105], v[112:113]
	v_pk_add_f32 v[100:101], v[100:101], v[108:109]
	v_pk_add_f32 v[98:99], v[98:99], v[106:107]
	v_pk_add_f32 v[100:101], v[100:101], v[104:105]
	v_pk_add_f32 v[98:99], v[98:99], v[102:103]
	s_nop 0
	v_pk_mov_b32 v[102:103], v[98:99], v[100:101] op_sel:[1,0]
	v_mov_b32_e32 v99, v101
	v_pk_add_f32 v[98:99], v[102:103], v[98:99]
	s_nop 0
	v_pk_add_f32 v[98:99], v[98:99], v[98:99] op_sel:[0,1] op_sel_hi:[1,0]
	s_nop 0
	v_mov_b32_e32 v99, v98
	s_nop 1
	v_permlane32_swap_b32_e32 v98, v99
	v_add_f32_e32 v99, v98, v99
	v_mov_b32_e32 v98, 0
	v_cmp_lt_f32_e32 vcc, 0, v99
	s_and_saveexec_b64 s[4:5], vcc
	s_cbranch_execz .LBB0_484
	s_waitcnt vmcnt(0)
	v_mov_b32_e32 v98, v239

;     ...
;         const float sc = l > 0.f ? gp[2] / l : 0.f;
; #pragma unroll
;         for (int dt = 0; dt < 2; ++dt)
; #pragma unroll
;             for (int i = 0; i < 16; ++i) oacc[dt][i] += sc * o[dt][i];
	v_div_scale_f32 v100, s[2:3], v99, v99, v98
	v_rcp_f32_e32 v101, v100
	v_div_scale_f32 v102, vcc, v98, v99, v98
	v_fma_f32 v103, -v100, v101, 1.0
	v_fmac_f32_e32 v101, v103, v101
	v_mul_f32_e32 v103, v102, v101
	v_fma_f32 v104, -v100, v103, v102
	v_fmac_f32_e32 v103, v104, v101
	v_fma_f32 v100, -v100, v103, v102
	v_div_fmas_f32 v100, v100, v101, v103
	v_div_fixup_f32 v98, v100, v99, v98
	s_branch .LBB0_484
